# SSD cumulative-decay scan via DPP row_shr/row_bcast instead of 6 ds_bpermute round trips (f32, different summation association)
# baseline (speedup 1.0000x reference)
; __device__ __forceinline__ void phase_ssd(KP P, char* smem, const int wv) {
;     ...
;       float a63;
;       {
;         float ac = dtv * A_h;
; #pragma unroll
;         for (int o = 1; o < 64; o <<= 1) {
;           float t = shup(ac, o, lane);
;           if (lane >= o) ac += t;
;         }
;         a63 = shidx(ac, 63);
;         myAc[lane] = ac;
;         myDt[lane] = dtv;
;         myW[lane] = __expf(a63 - ac) * dtv;
;       }
;       lds_barrier();
;       if (c + 1 < nch) {
;         const int r1 = r0 + 64;
;         int rsl = rs;
;         asm volatile("" : "+v"(rsl));
;         if (conv_role) {
;           const bfu* zxc = zx + ((size_t)r1 - 3) * ZXW + DI;
; #pragma unroll
;           for (int k = 0; k < 11; ++k) pre[k] = *(const u32x4*)(zxc + (unsigned)((rsl * 8 + k) * ZXW + cc));
;         } else {
;           const bfu* zsrc = zx + (size_t)(r1 + zrow) * ZXW + (g * 8 + hp * 2) * 64 + zhalf * 64;
; #pragma unroll
;           for (int k = 0; k < 8; ++k) pre[k] = *(const u32x4*)(zsrc + k * 8);
;         }
;         dtv = dtb[(size_t)(r1 + lane) * 32 + head];
.LBB0_423:
	s_waitcnt vmcnt(0)
	v_mul_f32_e64 v0, v145, -v143
	s_lshl_b32 s48, s89, 6
	s_add_i32 s48, s48, s85
	s_add_i32 s89, s89, 1
	s_cmp_ge_u32 s89, s88
	v_add_f32_dpp v0, v0, v0 row_shr:1 row_mask:0xf bank_mask:0xf bound_ctrl:1
	s_nop 1
	v_add_f32_dpp v0, v0, v0 row_shr:2 row_mask:0xf bank_mask:0xf bound_ctrl:1
	s_nop 1
	v_add_f32_dpp v0, v0, v0 row_shr:4 row_mask:0xf bank_mask:0xf bound_ctrl:1
	s_nop 1
	v_add_f32_dpp v0, v0, v0 row_shr:8 row_mask:0xf bank_mask:0xf bound_ctrl:1
	s_nop 1
	v_add_f32_dpp v0, v0, v0 row_bcast:15 row_mask:0xa bank_mask:0xf
	s_nop 1
	v_add_f32_dpp v0, v0, v0 row_bcast:31 row_mask:0xc bank_mask:0xf
	ds_write_b32 v183, v0
	ds_write_b32 v184, v145
	v_readlane_b32 s49, v0, 63
	s_nop 1
	v_sub_f32_e32 v0, s49, v0
	v_mul_f32_e32 v0, 0x3fb8aa3b, v0
	v_exp_f32_e32 v0, v0
	s_nop 0
	v_mul_f32_e32 v0, v145, v0
	ds_write_b32 v185, v0
	s_waitcnt lgkmcnt(0)
	s_barrier
	s_cbranch_scc1 .LBB0_429
	s_add_i32 s36, s48, 64
	v_mov_b32_e32 v0, v149
	s_mov_b64 s[34:35], -1
	s_and_b64 vcc, exec, s[68:69]
	s_cbranch_vccz .LBB0_426
	v_add_u32_e32 v36, s36, v117
	s_movk_i32 s34, 0x2800
	v_mad_i64_i32 v[36:37], s[34:35], v36, s34, v[2:3]
	s_mov_b64 s[34:35], 0x50
	s_nop 0
	v_lshl_add_u64 v[56:57], v[36:37], 0, s[34:35]
	s_mov_b64 s[34:35], 0x60
	v_lshl_add_u64 v[60:61], v[36:37], 0, s[34:35]
	s_mov_b64 s[34:35], 0x70
	v_lshl_add_u64 v[40:41], v[36:37], 0, 16
	v_lshl_add_u64 v[44:45], v[36:37], 0, 32
	v_lshl_add_u64 v[48:49], v[36:37], 0, 48
	v_lshl_add_u64 v[52:53], v[36:37], 0, 64
	v_lshl_add_u64 v[64:65], v[36:37], 0, s[34:35]
	s_mov_b64 s[34:35], 0
